# re-measure of best_v22 (K1 saddr DMA + own first barrier + no setprio + merged waits), unchanged bytes
# baseline (speedup 1.0000x reference)
; #define PG8_STAGE(bufoff, gbase, voff) do { _Pragma("unroll") for (int _i = 0; _i < 2; ++_i) \
;         __builtin_amdgcn_global_load_lds((const unsigned*)((const char*)(gbase) + (voff)[_i]), (PG8_LAS unsigned*)(lds + (bufoff) + ldsw + _i * 8192), 16, 0, 0); } while (0)
; #define PG8_LDA(dst, b, h) do { _Pragma("unroll") for (int m = 0; m < 4; ++m) _Pragma("unroll") for (int k = 0; k < 2; ++k) dst[m][k] = *(const PG8_LAS bf16x8*)(lds + PG8_SA(b, h) + aoff + m * 2048 + k * 1024); } while (0)
; #define PG8_LDB(dst, b, h) do { _Pragma("unroll") for (int n = 0; n < 2; ++n) _Pragma("unroll") for (int k = 0; k < 2; ++k) dst[n][k] = *(const PG8_LAS bf16x8*)(lds + PG8_SB(b, h) + boff + n * 2048 + k * 1024); } while (0)
; #define PG8_WAIT_V(n) asm volatile("s_waitcnt vmcnt(" #n ")" ::: "memory")
; #define PG8_WAIT_L(n) asm volatile("s_waitcnt lgkmcnt(" #n ")" ::: "memory")
; #define PG8_BAR __builtin_amdgcn_s_barrier()
; #define PG8_SCHED __builtin_amdgcn_sched_barrier(0)
; template <class Epi, class Sched, bool ALIGN_EPI = false, bool SP2 = false>
; __device__ __forceinline__ void gemm_phase(PG8_LAS unsigned char* lds, const Gemm g, const Sched& S, const Epi& E) {
;     ...
;             const bool last = (t == nt - 2);
;             const char* a1 = cA + (size_t)(t + 1) * kstep;
;             const char* a2 = last ? nA : cA + (size_t)(t + 2) * kstep; const char* b2 = last ? nB : cB + (size_t)(t + 2) * kstep;
;             const char* a3 = a2 + kstep; const char* b3 = b2 + kstep;
;             if (last && has_next) S.a_ready(nxt);
;             if constexpr (SP2) {
;             PG8_LDB(B0, 0, 0); PG8_LDB(B1, 0, 1); PG8_SCHED; PG8_LDA(At, 0, 0); PG8_STAGE(PG8_SA(1, 1), a1 + hstep, voffA);
;             PG8_WAIT_V(8); PG8_WAIT_L(0); PG8_BAR; PG8_MMA(0, 0, At, B0); PG8_MMA(0, 1, At, B1); PG8_BAR; PG8_SCHED;
;             PG8_LDA(At, 0, 1); PG8_STAGE(PG8_SB(0, 0), b2, voffB); PG8_STAGE(PG8_SB(0, 1), b2 + hstep, voffB); PG8_STAGE(PG8_SA(0, 0), a2, voffA);
;             PG8_WAIT_V(8); PG8_WAIT_L(0); PG8_BAR; PG8_MMA(1, 0, At, B0); PG8_MMA(1, 1, At, B1); PG8_BAR; PG8_SCHED;
;             PG8_LDB(B0, 1, 0); PG8_LDB(B1, 1, 1); PG8_SCHED; PG8_LDA(At, 1, 0); PG8_STAGE(PG8_SA(0, 1), a2 + hstep, voffA);
;             PG8_WAIT_V(8); PG8_WAIT_L(0); PG8_BAR; PG8_MMA(0, 0, At, B0); PG8_MMA(0, 1, At, B1); PG8_BAR; PG8_SCHED;
.LBB0_1356:
	s_add_u32 s20, s18, 0x4000
	s_addc_u32 s21, s19, 0
	s_cmp_eq_u32 s68, 12
	s_cselect_b32 s64, s40, s20
	s_cselect_b32 s65, s11, s21
	s_cselect_b32 s62, s61, s66
	s_cselect_b32 s63, s9, s67
	s_add_u32 s20, s64, 0x8000
	s_addc_u32 s21, s65, 0
	s_add_i32 s69, 0, 0x10000
	s_add_i32 s72, 0, 0x14000
	v_add_u32_e32 v140, s69, v162
	v_add_u32_e32 v160, s72, v162
	ds_read_b128 v[128:131], v140
	ds_read_b128 v[132:135], v140 offset:1024
	ds_read_b128 v[136:139], v140 offset:2048
	ds_read_b128 v[140:143], v140 offset:3072
	ds_read_b128 v[156:159], v160
	ds_read_b128 v[164:167], v160 offset:1024
	ds_read_b128 v[168:171], v160 offset:2048
	ds_read_b128 v[172:175], v160 offset:3072
	s_add_i32 m0, s37, 0xc000
	ds_read_b128 v[176:179], v163
	ds_read_b128 v[180:183], v163 offset:1024
	ds_read_b128 v[184:187], v163 offset:2048
	ds_read_b128 v[188:191], v163 offset:3072
	ds_read_b128 v[192:195], v163 offset:4096
	ds_read_b128 v[196:199], v163 offset:5120
	ds_read_b128 v[200:203], v163 offset:6144
	ds_read_b128 v[204:207], v163 offset:7168
	global_load_lds_dwordx4 v152, s[18:19]
	s_add_i32 m0, s37, 0xe000
	s_nop 0
	global_load_lds_dwordx4 v154, s[18:19]
	s_waitcnt vmcnt(8) lgkmcnt(0)
	s_barrier
	v_mfma_f32_16x16x32_bf16 v[124:127], v[128:131], v[176:179], v[124:127]
	v_mfma_f32_16x16x32_bf16 v[108:111], v[128:131], v[184:187], v[108:111]
	v_mfma_f32_16x16x32_bf16 v[92:95], v[128:131], v[192:195], v[92:95]
	v_mfma_f32_16x16x32_bf16 v[76:79], v[128:131], v[200:203], v[76:79]
	v_mfma_f32_16x16x32_bf16 v[120:123], v[136:139], v[176:179], v[120:123]
	v_mfma_f32_16x16x32_bf16 v[104:107], v[136:139], v[184:187], v[104:107]
	v_mfma_f32_16x16x32_bf16 v[88:91], v[136:139], v[192:195], v[88:91]
	v_mfma_f32_16x16x32_bf16 v[72:75], v[136:139], v[200:203], v[72:75]
	v_mfma_f32_16x16x32_bf16 v[124:127], v[132:135], v[180:183], v[124:127]
	v_mfma_f32_16x16x32_bf16 v[108:111], v[132:135], v[188:191], v[108:111]
	v_mfma_f32_16x16x32_bf16 v[92:95], v[132:135], v[196:199], v[92:95]
	v_mfma_f32_16x16x32_bf16 v[76:79], v[132:135], v[204:207], v[76:79]
	v_mfma_f32_16x16x32_bf16 v[120:123], v[140:143], v[180:183], v[120:123]
	v_mfma_f32_16x16x32_bf16 v[104:107], v[140:143], v[188:191], v[104:107]
	v_mfma_f32_16x16x32_bf16 v[88:91], v[140:143], v[196:199], v[88:91]
	v_mfma_f32_16x16x32_bf16 v[72:75], v[140:143], v[204:207], v[72:75]
	v_mfma_f32_16x16x32_bf16 v[116:119], v[156:159], v[176:179], v[116:119]
	v_mfma_f32_16x16x32_bf16 v[100:103], v[156:159], v[184:187], v[100:103]
	v_mfma_f32_16x16x32_bf16 v[84:87], v[156:159], v[192:195], v[84:87]
	v_mfma_f32_16x16x32_bf16 v[68:71], v[156:159], v[200:203], v[68:71]
	v_mfma_f32_16x16x32_bf16 v[112:115], v[168:171], v[176:179], v[112:115]
	v_mfma_f32_16x16x32_bf16 v[96:99], v[168:171], v[184:187], v[96:99]
	v_mfma_f32_16x16x32_bf16 v[80:83], v[168:171], v[192:195], v[80:83]
	v_mfma_f32_16x16x32_bf16 v[64:67], v[168:171], v[200:203], v[64:67]
	v_mfma_f32_16x16x32_bf16 v[116:119], v[164:167], v[180:183], v[116:119]
	v_mfma_f32_16x16x32_bf16 v[100:103], v[164:167], v[188:191], v[100:103]
	v_mfma_f32_16x16x32_bf16 v[84:87], v[164:167], v[196:199], v[84:87]
	v_mfma_f32_16x16x32_bf16 v[68:71], v[164:167], v[204:207], v[68:71]
	v_mfma_f32_16x16x32_bf16 v[112:115], v[172:175], v[180:183], v[112:115]
	v_mfma_f32_16x16x32_bf16 v[96:99], v[172:175], v[188:191], v[96:99]
	v_mfma_f32_16x16x32_bf16 v[80:83], v[172:175], v[196:199], v[80:83]
	v_mfma_f32_16x16x32_bf16 v[64:67], v[172:175], v[204:207], v[64:67]
	s_barrier
	s_add_i32 s69, s69, s30
	s_mov_b32 m0, s69
	ds_read_b128 v[176:179], v163 offset:16384
	ds_read_b128 v[180:183], v163 offset:17408
	ds_read_b128 v[184:187], v163 offset:18432
	ds_read_b128 v[188:191], v163 offset:19456
	ds_read_b128 v[192:195], v163 offset:20480
	ds_read_b128 v[196:199], v163 offset:21504
	ds_read_b128 v[200:203], v163 offset:22528
	ds_read_b128 v[204:207], v163 offset:23552
	global_load_lds_dwordx4 v148, s[62:63]
	s_add_i32 m0, s69, 0x2000
	s_add_u32 s70, s62, 0x4000
	s_addc_u32 s71, s63, 0
	s_add_i32 s69, s72, s30
	global_load_lds_dwordx4 v144, s[62:63]
	s_mov_b32 m0, s69
	s_nop 0
	global_load_lds_dwordx4 v148, s[70:71]
	s_add_i32 m0, s69, 0x2000
	s_nop 0
	global_load_lds_dwordx4 v144, s[70:71]
	s_mov_b32 m0, s37
	s_nop 0
	global_load_lds_dwordx4 v150, s[64:65]
	s_mov_b32 m0, s39
	s_nop 0
	global_load_lds_dwordx4 v146, s[64:65]
	s_waitcnt vmcnt(8) lgkmcnt(0)
	s_barrier
	v_mfma_f32_16x16x32_bf16 v[60:63], v[128:131], v[176:179], v[60:63]
	v_mfma_f32_16x16x32_bf16 v[44:47], v[128:131], v[184:187], v[44:47]
	v_mfma_f32_16x16x32_bf16 v[28:31], v[128:131], v[192:195], v[28:31]
	v_mfma_f32_16x16x32_bf16 v[12:15], v[128:131], v[200:203], v[12:15]
	v_mfma_f32_16x16x32_bf16 v[56:59], v[136:139], v[176:179], v[56:59]
	v_mfma_f32_16x16x32_bf16 v[40:43], v[136:139], v[184:187], v[40:43]
	v_mfma_f32_16x16x32_bf16 v[24:27], v[136:139], v[192:195], v[24:27]
	v_mfma_f32_16x16x32_bf16 v[8:11], v[136:139], v[200:203], v[8:11]
	v_mfma_f32_16x16x32_bf16 v[60:63], v[132:135], v[180:183], v[60:63]
	v_mfma_f32_16x16x32_bf16 v[44:47], v[132:135], v[188:191], v[44:47]
	v_mfma_f32_16x16x32_bf16 v[28:31], v[132:135], v[196:199], v[28:31]
	v_mfma_f32_16x16x32_bf16 v[12:15], v[132:135], v[204:207], v[12:15]
	v_mfma_f32_16x16x32_bf16 v[56:59], v[140:143], v[180:183], v[56:59]
	v_mfma_f32_16x16x32_bf16 v[40:43], v[140:143], v[188:191], v[40:43]
	v_mfma_f32_16x16x32_bf16 v[24:27], v[140:143], v[196:199], v[24:27]
	v_mfma_f32_16x16x32_bf16 v[8:11], v[140:143], v[204:207], v[8:11]
	v_mfma_f32_16x16x32_bf16 v[52:55], v[156:159], v[176:179], v[52:55]
	v_mfma_f32_16x16x32_bf16 v[36:39], v[156:159], v[184:187], v[36:39]
	v_mfma_f32_16x16x32_bf16 v[20:23], v[156:159], v[192:195], v[20:23]
	v_mfma_f32_16x16x32_bf16 v[4:7], v[156:159], v[200:203], v[4:7]
	v_mfma_f32_16x16x32_bf16 v[48:51], v[168:171], v[176:179], v[48:51]
	v_mfma_f32_16x16x32_bf16 v[32:35], v[168:171], v[184:187], v[32:35]
	v_mfma_f32_16x16x32_bf16 v[16:19], v[168:171], v[192:195], v[16:19]
	v_mfma_f32_16x16x32_bf16 v[0:3], v[168:171], v[200:203], v[0:3]
	v_mfma_f32_16x16x32_bf16 v[52:55], v[164:167], v[180:183], v[52:55]
	v_mfma_f32_16x16x32_bf16 v[36:39], v[164:167], v[188:191], v[36:39]
	v_mfma_f32_16x16x32_bf16 v[20:23], v[164:167], v[196:199], v[20:23]
	v_mfma_f32_16x16x32_bf16 v[4:7], v[164:167], v[204:207], v[4:7]
	v_mfma_f32_16x16x32_bf16 v[48:51], v[172:175], v[180:183], v[48:51]
	v_mfma_f32_16x16x32_bf16 v[32:35], v[172:175], v[188:191], v[32:35]
	v_mfma_f32_16x16x32_bf16 v[16:19], v[172:175], v[196:199], v[16:19]
	v_mfma_f32_16x16x32_bf16 v[0:3], v[172:175], v[204:207], v[0:3]
	s_barrier
; #define PG8_STAGE(bufoff, gbase, voff) do { _Pragma("unroll") for (int _i = 0; _i < 2; ++_i) \
;         __builtin_amdgcn_global_load_lds((const unsigned*)((const char*)(gbase) + (voff)[_i]), (PG8_LAS unsigned*)(lds + (bufoff) + ldsw + _i * 8192), 16, 0, 0); } while (0)
; #define PG8_LDA(dst, b, h) do { _Pragma("unroll") for (int m = 0; m < 4; ++m) _Pragma("unroll") for (int k = 0; k < 2; ++k) dst[m][k] = *(const PG8_LAS bf16x8*)(lds + PG8_SA(b, h) + aoff + m * 2048 + k * 1024); } while (0)
; #define PG8_LDB(dst, b, h) do { _Pragma("unroll") for (int n = 0; n < 2; ++n) _Pragma("unroll") for (int k = 0; k < 2; ++k) dst[n][k] = *(const PG8_LAS bf16x8*)(lds + PG8_SB(b, h) + boff + n * 2048 + k * 1024); } while (0)
; #define PG8_MMA(ai, bj, At, Bt) do { __builtin_amdgcn_s_setprio(1); _Pragma("unroll") for (int m = 0; m < 4; ++m) _Pragma("unroll") for (int n = 0; n < 2; ++n) _Pragma("unroll") for (int k = 0; k < 2; ++k) \
;         acc[ai][bj][m][n] = __builtin_amdgcn_mfma_f32_16x16x32_bf16(Bt[n][k], At[m][k], acc[ai][bj][m][n], 0, 0, 0); __builtin_amdgcn_s_setprio(0); } while (0)
; #define PG8_WAIT_V(n) asm volatile("s_waitcnt vmcnt(" #n ")" ::: "memory")
; #define PG8_WAIT_L(n) asm volatile("s_waitcnt lgkmcnt(" #n ")" ::: "memory")
; #define PG8_BAR __builtin_amdgcn_s_barrier()
; #define PG8_SCHED __builtin_amdgcn_sched_barrier(0)
; template <class Epi, class Sched, bool ALIGN_EPI = false, bool SP2 = false>
; __device__ __forceinline__ void gemm_phase(PG8_LAS unsigned char* lds, const Gemm g, const Sched& S, const Epi& E) {
;     ...
;             PG8_LDB(B0, 1, 0); PG8_LDB(B1, 1, 1); PG8_SCHED; PG8_LDA(At, 1, 0); PG8_STAGE(PG8_SA(0, 1), a2 + hstep, voffA);
;             PG8_WAIT_V(8); PG8_WAIT_L(0); PG8_BAR; PG8_MMA(0, 0, At, B0); PG8_MMA(0, 1, At, B1); PG8_BAR; PG8_SCHED;
;             PG8_LDA(At, 1, 1); PG8_STAGE(PG8_SB(1, 0), b3, voffB); PG8_STAGE(PG8_SB(1, 1), b3 + hstep, voffB); PG8_STAGE(PG8_SA(1, 0), a3, voffA);
;             PG8_WAIT_V(8); PG8_WAIT_L(0); PG8_BAR; PG8_MMA(1, 0, At, B0); PG8_MMA(1, 1, At, B1); PG8_BAR; PG8_SCHED;
;     ...
;         if constexpr (ALIGN_EPI) { if (wr == 0) PG8_BAR; }
	s_add_i32 s69, 0, 0x18000
	s_add_i32 s70, 0, 0x1c000
	v_add_u32_e32 v140, s69, v162
	v_add_u32_e32 v160, s70, v162
	ds_read_b128 v[128:131], v140
	ds_read_b128 v[132:135], v140 offset:1024
	ds_read_b128 v[136:139], v140 offset:2048
	ds_read_b128 v[140:143], v140 offset:3072
	ds_read_b128 v[156:159], v160
	ds_read_b128 v[164:167], v160 offset:1024
	ds_read_b128 v[168:171], v160 offset:2048
	ds_read_b128 v[172:175], v160 offset:3072
	s_add_u32 s64, s64, 0x4000
	s_addc_u32 s65, s65, 0
	s_mov_b32 m0, s41
	ds_read_b128 v[176:179], v163 offset:32768
	ds_read_b128 v[180:183], v163 offset:33792
	ds_read_b128 v[184:187], v163 offset:34816
	ds_read_b128 v[188:191], v163 offset:35840
	ds_read_b128 v[192:195], v163 offset:36864
	ds_read_b128 v[196:199], v163 offset:37888
	ds_read_b128 v[200:203], v163 offset:38912
	ds_read_b128 v[204:207], v163 offset:39936
	global_load_lds_dwordx4 v150, s[64:65]
	s_mov_b32 m0, s42
	s_nop 0
	global_load_lds_dwordx4 v146, s[64:65]
	s_waitcnt vmcnt(8) lgkmcnt(0)
	s_barrier
	v_mfma_f32_16x16x32_bf16 v[124:127], v[128:131], v[176:179], v[124:127]
	v_mfma_f32_16x16x32_bf16 v[108:111], v[128:131], v[184:187], v[108:111]
	v_mfma_f32_16x16x32_bf16 v[92:95], v[128:131], v[192:195], v[92:95]
	v_mfma_f32_16x16x32_bf16 v[76:79], v[128:131], v[200:203], v[76:79]
	v_mfma_f32_16x16x32_bf16 v[120:123], v[136:139], v[176:179], v[120:123]
	v_mfma_f32_16x16x32_bf16 v[104:107], v[136:139], v[184:187], v[104:107]
	v_mfma_f32_16x16x32_bf16 v[88:91], v[136:139], v[192:195], v[88:91]
	v_mfma_f32_16x16x32_bf16 v[72:75], v[136:139], v[200:203], v[72:75]
	v_mfma_f32_16x16x32_bf16 v[124:127], v[132:135], v[180:183], v[124:127]
	v_mfma_f32_16x16x32_bf16 v[108:111], v[132:135], v[188:191], v[108:111]
	v_mfma_f32_16x16x32_bf16 v[92:95], v[132:135], v[196:199], v[92:95]
	v_mfma_f32_16x16x32_bf16 v[76:79], v[132:135], v[204:207], v[76:79]
	v_mfma_f32_16x16x32_bf16 v[120:123], v[140:143], v[180:183], v[120:123]
	v_mfma_f32_16x16x32_bf16 v[104:107], v[140:143], v[188:191], v[104:107]
	v_mfma_f32_16x16x32_bf16 v[88:91], v[140:143], v[196:199], v[88:91]
	v_mfma_f32_16x16x32_bf16 v[72:75], v[140:143], v[204:207], v[72:75]
	v_mfma_f32_16x16x32_bf16 v[116:119], v[156:159], v[176:179], v[116:119]
	v_mfma_f32_16x16x32_bf16 v[100:103], v[156:159], v[184:187], v[100:103]
	v_mfma_f32_16x16x32_bf16 v[84:87], v[156:159], v[192:195], v[84:87]
	v_mfma_f32_16x16x32_bf16 v[68:71], v[156:159], v[200:203], v[68:71]
	v_mfma_f32_16x16x32_bf16 v[112:115], v[168:171], v[176:179], v[112:115]
	v_mfma_f32_16x16x32_bf16 v[96:99], v[168:171], v[184:187], v[96:99]
	v_mfma_f32_16x16x32_bf16 v[80:83], v[168:171], v[192:195], v[80:83]
	v_mfma_f32_16x16x32_bf16 v[64:67], v[168:171], v[200:203], v[64:67]
	v_mfma_f32_16x16x32_bf16 v[116:119], v[164:167], v[180:183], v[116:119]
	v_mfma_f32_16x16x32_bf16 v[100:103], v[164:167], v[188:191], v[100:103]
	v_mfma_f32_16x16x32_bf16 v[84:87], v[164:167], v[196:199], v[84:87]
	v_mfma_f32_16x16x32_bf16 v[68:71], v[164:167], v[204:207], v[68:71]
	v_mfma_f32_16x16x32_bf16 v[112:115], v[172:175], v[180:183], v[112:115]
	v_mfma_f32_16x16x32_bf16 v[96:99], v[172:175], v[188:191], v[96:99]
	v_mfma_f32_16x16x32_bf16 v[80:83], v[172:175], v[196:199], v[80:83]
	v_mfma_f32_16x16x32_bf16 v[64:67], v[172:175], v[204:207], v[64:67]
	s_barrier
	s_add_u32 s64, s62, 0x8000
	s_addc_u32 s65, s63, 0
	s_add_i32 s69, s69, s30
	s_mov_b32 m0, s69
	ds_read_b128 v[176:179], v163 offset:49152
	ds_read_b128 v[180:183], v163 offset:50176
	ds_read_b128 v[184:187], v163 offset:51200
	ds_read_b128 v[188:191], v163 offset:52224
	ds_read_b128 v[192:195], v163 offset:53248
	ds_read_b128 v[196:199], v163 offset:54272
	ds_read_b128 v[200:203], v163 offset:55296
	ds_read_b128 v[204:207], v163 offset:56320
	global_load_lds_dwordx4 v148, s[64:65]
	s_add_i32 m0, s69, 0x2000
	s_add_u32 s62, s62, 0xc000
	v_lshl_add_u64 v[160:161], s[64:65], 0, v[144:145]
	s_addc_u32 s63, s63, 0
	s_add_i32 s64, s70, s30
	global_load_lds_dwordx4 v[160:161], off
	s_mov_b32 m0, s64
	s_nop 0
	global_load_lds_dwordx4 v148, s[62:63]
	s_add_i32 m0, s64, 0x2000
	s_nop 0
	global_load_lds_dwordx4 v144, s[62:63]
	s_mov_b32 m0, s54
	s_nop 0
	global_load_lds_dwordx4 v150, s[20:21]
	s_mov_b32 m0, s55
	s_nop 0
	global_load_lds_dwordx4 v146, s[20:21]
	s_waitcnt vmcnt(8) lgkmcnt(0)
	s_barrier
	v_mfma_f32_16x16x32_bf16 v[60:63], v[128:131], v[176:179], v[60:63]
	v_mfma_f32_16x16x32_bf16 v[44:47], v[128:131], v[184:187], v[44:47]
	v_mfma_f32_16x16x32_bf16 v[28:31], v[128:131], v[192:195], v[28:31]
	v_mfma_f32_16x16x32_bf16 v[12:15], v[128:131], v[200:203], v[12:15]
	v_mfma_f32_16x16x32_bf16 v[56:59], v[136:139], v[176:179], v[56:59]
	v_mfma_f32_16x16x32_bf16 v[40:43], v[136:139], v[184:187], v[40:43]
	v_mfma_f32_16x16x32_bf16 v[24:27], v[136:139], v[192:195], v[24:27]
	v_mfma_f32_16x16x32_bf16 v[8:11], v[136:139], v[200:203], v[8:11]
	v_mfma_f32_16x16x32_bf16 v[60:63], v[132:135], v[180:183], v[60:63]
	v_mfma_f32_16x16x32_bf16 v[44:47], v[132:135], v[188:191], v[44:47]
	v_mfma_f32_16x16x32_bf16 v[28:31], v[132:135], v[196:199], v[28:31]
	v_mfma_f32_16x16x32_bf16 v[12:15], v[132:135], v[204:207], v[12:15]
	v_mfma_f32_16x16x32_bf16 v[56:59], v[140:143], v[180:183], v[56:59]
	v_mfma_f32_16x16x32_bf16 v[40:43], v[140:143], v[188:191], v[40:43]
	v_mfma_f32_16x16x32_bf16 v[24:27], v[140:143], v[196:199], v[24:27]
	v_mfma_f32_16x16x32_bf16 v[8:11], v[140:143], v[204:207], v[8:11]
	v_mfma_f32_16x16x32_bf16 v[52:55], v[156:159], v[176:179], v[52:55]
	v_mfma_f32_16x16x32_bf16 v[36:39], v[156:159], v[184:187], v[36:39]
	v_mfma_f32_16x16x32_bf16 v[20:23], v[156:159], v[192:195], v[20:23]
	v_mfma_f32_16x16x32_bf16 v[4:7], v[156:159], v[200:203], v[4:7]
	v_mfma_f32_16x16x32_bf16 v[48:51], v[168:171], v[176:179], v[48:51]
	v_mfma_f32_16x16x32_bf16 v[32:35], v[168:171], v[184:187], v[32:35]
	v_mfma_f32_16x16x32_bf16 v[16:19], v[168:171], v[192:195], v[16:19]
	v_mfma_f32_16x16x32_bf16 v[0:3], v[168:171], v[200:203], v[0:3]
	v_mfma_f32_16x16x32_bf16 v[52:55], v[164:167], v[180:183], v[52:55]
	v_mfma_f32_16x16x32_bf16 v[36:39], v[164:167], v[188:191], v[36:39]
	v_mfma_f32_16x16x32_bf16 v[20:23], v[164:167], v[196:199], v[20:23]
	v_mfma_f32_16x16x32_bf16 v[4:7], v[164:167], v[204:207], v[4:7]
	v_mfma_f32_16x16x32_bf16 v[48:51], v[172:175], v[180:183], v[48:51]
	v_mfma_f32_16x16x32_bf16 v[32:35], v[172:175], v[188:191], v[32:35]
	v_mfma_f32_16x16x32_bf16 v[16:19], v[172:175], v[196:199], v[16:19]
	v_mfma_f32_16x16x32_bf16 v[0:3], v[172:175], v[204:207], v[0:3]
	s_barrier
	s_add_i32 s68, s68, 2
	s_add_u32 s18, s18, 0x10000
	s_addc_u32 s19, s19, 0
	s_add_u32 s66, s66, 0x10000
	s_addc_u32 s67, s67, 0
	s_cmp_gt_u32 s68, 13
	s_cbranch_scc0 .LBB0_1356
	s_and_b64 vcc, exec, s[6:7]
	s_cbranch_vccz .LBB0_1359
	s_barrier
